# GEMM K-loop heads of A,C,D,E,F aligned to 64 bytes
# speedup vs baseline: 1.0017x; 1.0017x over previous
.LBB0_412:
	s_add_u32 s78, s8, 0x100
	s_addc_u32 s1, s9, 0
	s_ashr_i32 s53, s52, 31
	s_lshl_b64 s[4:5], s[52:53], 19
	s_add_u32 s58, s14, s4
	s_addc_u32 s59, s15, s5
	s_and_b64 s[4:5], s[2:3], exec
	s_cselect_b32 s4, s59, s55
	s_cselect_b32 s5, s58, s54
	s_ashr_i32 s83, s82, 31
	s_lshl_b64 s[10:11], s[82:83], 19
	v_readlane_b32 s12, v251, 26
	s_add_u32 s26, s12, s10
	v_readlane_b32 s10, v250, 6
	s_addc_u32 s27, s10, s11
	s_and_b64 s[10:11], s[2:3], exec
	s_cselect_b32 s12, s27, s9
	s_cselect_b32 s13, s26, s8
	s_add_u32 s8, s54, 0x40080
	s_addc_u32 s9, s55, 0
	v_lshl_add_u64 v[132:133], s[8:9], 0, v[190:191]
	v_lshl_add_u64 v[134:135], s[8:9], 0, v[192:193]
	s_mov_b32 s17, -2
	s_mov_b64 s[8:9], 0
	.p2align	6

.LBB0_1310:
	s_ashr_i32 s25, s24, 31
	s_xor_b64 s[52:53], s[14:15], -1
	s_lshl_b64 s[4:5], s[24:25], 19
	v_readlane_b32 s8, v250, 39
	s_add_u32 s42, s8, s4
	v_readlane_b32 s4, v250, 41
	s_addc_u32 s43, s4, s5
	s_and_b64 s[4:5], s[40:41], exec
	s_cselect_b32 s13, s43, s51
	s_cselect_b32 s78, s42, s50
	s_ashr_i32 s27, s26, 31
	s_lshl_b64 s[4:5], s[26:27], 19
	s_add_u32 s44, s65, s4
	v_readlane_b32 s4, v250, 45
	s_addc_u32 s45, s4, s5
	s_and_b64 s[4:5], s[40:41], exec
	s_cselect_b32 s9, s45, s11
	s_cselect_b32 s79, s44, s10
	s_ashr_i32 s4, s24, 1
	s_ashr_i32 s5, s4, 31
	s_lshl_b64 s[4:5], s[4:5], 15
	v_readlane_b32 s8, v250, 12
	s_add_u32 s46, s8, s4
	v_readlane_b32 s4, v251, 21
	s_addc_u32 s47, s4, s5
	s_and_b64 s[4:5], s[40:41], exec
	s_cselect_b32 s18, s47, s49
	s_cselect_b32 s30, s46, s48
	s_lshl_b32 s4, s38, 3
	s_and_b32 s25, s4, -16
	s_lshl_b32 s4, s54, 8
	s_lshl_b32 s5, s38, 7
	v_readlane_b32 s8, v250, 49
	s_and_b32 s5, s5, 0x80
	s_add_i32 s27, s8, s4
	s_add_i32 s27, s27, s5
	s_lshl_b32 s5, s38, 8
	v_readlane_b32 s8, v250, 47
	s_addk_i32 s25, 0x4000
	s_add_i32 s5, s5, s8
	s_or_b32 s8, s4, s73
	v_lshl_add_u64 v[2:3], s[48:49], 0, v[204:205]
	v_mov_b32_e32 v14, v15
	v_mov_b32_e32 v16, v15
	v_mov_b32_e32 v17, v15
	v_lshl_add_u64 v[206:207], v[2:3], 0, s[34:35]
	s_add_u32 s4, s10, 0x100
	v_mov_b64_e32 v[6:7], v[14:15]
	v_mov_b64_e32 v[10:11], v[14:15]
	v_mov_b64_e32 v[28:29], v[16:17]
	v_mov_b64_e32 v[32:33], v[16:17]
	v_mov_b64_e32 v[44:45], v[16:17]
	v_mov_b64_e32 v[48:49], v[16:17]
	v_mov_b64_e32 v[60:61], v[16:17]
	v_mov_b64_e32 v[64:65], v[16:17]
	v_mov_b64_e32 v[20:21], v[16:17]
	v_mov_b64_e32 v[24:25], v[16:17]
	v_mov_b64_e32 v[36:37], v[16:17]
	v_mov_b64_e32 v[40:41], v[16:17]
	v_mov_b64_e32 v[52:53], v[16:17]
	v_mov_b64_e32 v[56:57], v[16:17]
	v_mov_b64_e32 v[68:69], v[16:17]
	v_mov_b64_e32 v[72:73], v[16:17]
	v_mov_b64_e32 v[76:77], v[16:17]
	v_mov_b64_e32 v[80:81], v[16:17]
	v_mov_b64_e32 v[92:93], v[16:17]
	v_mov_b64_e32 v[96:97], v[16:17]
	v_mov_b64_e32 v[108:109], v[16:17]
	v_mov_b64_e32 v[112:113], v[16:17]
	v_mov_b64_e32 v[124:125], v[16:17]
	v_mov_b64_e32 v[128:129], v[16:17]
	v_mov_b64_e32 v[84:85], v[16:17]
	v_mov_b64_e32 v[88:89], v[16:17]
	v_mov_b64_e32 v[100:101], v[16:17]
	v_mov_b64_e32 v[104:105], v[16:17]
	v_mov_b64_e32 v[116:117], v[16:17]
	v_mov_b64_e32 v[120:121], v[16:17]
	v_mov_b64_e32 v[132:133], v[16:17]
	v_mov_b64_e32 v[136:137], v[16:17]
	v_mov_b64_e32 v[2:3], v[14:15]
	s_addc_u32 s60, s11, 0
	s_mov_b32 s61, -2
	s_mov_b64 s[54:55], 0
	v_mov_b64_e32 v[8:9], v[16:17]
	v_mov_b64_e32 v[12:13], v[16:17]
	v_mov_b64_e32 v[26:27], v[14:15]
	v_mov_b64_e32 v[30:31], v[14:15]
	v_mov_b64_e32 v[42:43], v[14:15]
	v_mov_b64_e32 v[46:47], v[14:15]
	v_mov_b64_e32 v[58:59], v[14:15]
	v_mov_b64_e32 v[62:63], v[14:15]
	v_mov_b64_e32 v[18:19], v[14:15]
	v_mov_b64_e32 v[22:23], v[14:15]
	v_mov_b64_e32 v[34:35], v[14:15]
	v_mov_b64_e32 v[38:39], v[14:15]
	v_mov_b64_e32 v[50:51], v[14:15]
	v_mov_b64_e32 v[54:55], v[14:15]
	v_mov_b64_e32 v[66:67], v[14:15]
	v_mov_b64_e32 v[70:71], v[14:15]
	v_mov_b64_e32 v[74:75], v[14:15]
	v_mov_b64_e32 v[78:79], v[14:15]
	v_mov_b64_e32 v[90:91], v[14:15]
	v_mov_b64_e32 v[94:95], v[14:15]
	v_mov_b64_e32 v[106:107], v[14:15]
	v_mov_b64_e32 v[110:111], v[14:15]
	v_mov_b64_e32 v[122:123], v[14:15]
	v_mov_b64_e32 v[126:127], v[14:15]
	v_mov_b64_e32 v[82:83], v[14:15]
	v_mov_b64_e32 v[86:87], v[14:15]
	v_mov_b64_e32 v[98:99], v[14:15]
	v_mov_b64_e32 v[102:103], v[14:15]
	v_mov_b64_e32 v[114:115], v[14:15]
	v_mov_b64_e32 v[118:119], v[14:15]
	v_mov_b64_e32 v[130:131], v[14:15]
	v_mov_b64_e32 v[134:135], v[14:15]
	v_mov_b64_e32 v[4:5], v[16:17]
	s_branch .LBB0_1312
	.p2align	6

.LBB0_1415:
	s_ashr_i32 s49, s48, 31
	s_mov_b64 s[8:9], s[2:3]
	s_mov_b64 s[2:3], s[76:77]
	s_xor_b64 s[76:77], s[14:15], -1
	s_lshl_b64 s[14:15], s[48:49], 19
	v_readlane_b32 s54, v251, 3
	v_readlane_b32 s55, v251, 4
	s_add_u32 s54, s54, s14
	s_addc_u32 s55, s55, s15
	s_and_b64 s[14:15], s[52:53], exec
	s_cselect_b32 s4, s55, s93
	s_cselect_b32 s13, s54, s92
	s_ashr_i32 s51, s50, 31
	s_lshl_b64 s[14:15], s[50:51], 19
	v_readlane_b32 s18, v250, 49
	s_add_u32 s56, s18, s14
	v_readlane_b32 s14, v251, 17
	s_addc_u32 s57, s14, s15
	s_and_b64 s[14:15], s[52:53], exec
	s_cselect_b32 s18, s57, s39
	s_cselect_b32 s30, s56, s38
	s_ashr_i32 s14, s48, 1
	s_ashr_i32 s15, s14, 31
	s_lshl_b64 s[14:15], s[14:15], 15
	v_readlane_b32 s49, v253, 36
	s_add_u32 s58, s49, s14
	v_readlane_b32 s14, v253, 37
	s_addc_u32 s59, s14, s15
	s_and_b64 s[14:15], s[52:53], exec
	s_cselect_b32 s49, s59, s11
	s_cselect_b32 s51, s58, s10
	s_add_u32 s60, s92, 0x100
	s_addc_u32 s61, s93, 0
	s_add_u32 s62, s38, 0x100
	s_addc_u32 s63, s39, 0
	s_add_u32 s82, s10, 0x100
	s_addc_u32 s83, s11, 0
	v_mov_b32_e32 v14, v15
	v_readlane_b32 s72, v251, 24
	v_readlane_b32 s68, v250, 51
	s_add_u32 s92, s92, 0x40080
	v_mov_b32_e32 v16, v15
	v_mov_b32_e32 v17, v15
	v_mov_b32_e32 v6, 0
	v_mov_b64_e32 v[2:3], v[14:15]
	v_readlane_b32 s73, v251, 25
	v_readlane_b32 s69, v250, 52
	s_addc_u32 s93, s93, 0
	s_mov_b32 s64, -2
	v_mov_b64_e32 v[4:5], v[16:17]
	v_mov_b32_e32 v7, v6
	v_mov_b32_e32 v8, v6
	v_mov_b32_e32 v9, v6
	v_mov_b32_e32 v10, v6
	v_mov_b32_e32 v11, v6
	v_mov_b32_e32 v12, v6
	v_mov_b32_e32 v13, v6
	v_mov_b32_e32 v24, v6
	v_mov_b32_e32 v25, v6
	v_mov_b32_e32 v26, v6
	v_mov_b32_e32 v27, v6
	v_mov_b32_e32 v28, v6
	v_mov_b32_e32 v29, v6
	v_mov_b32_e32 v30, v6
	v_mov_b32_e32 v31, v6
	v_mov_b32_e32 v40, v6
	v_mov_b32_e32 v41, v6
	v_mov_b32_e32 v42, v6
	v_mov_b32_e32 v43, v6
	v_mov_b32_e32 v44, v6
	v_mov_b32_e32 v45, v6
	v_mov_b32_e32 v46, v6
	v_mov_b32_e32 v47, v6
	v_mov_b32_e32 v56, v6
	v_mov_b32_e32 v57, v6
	v_mov_b32_e32 v58, v6
	v_mov_b32_e32 v59, v6
	v_mov_b32_e32 v60, v6
	v_mov_b32_e32 v61, v6
	v_mov_b32_e32 v62, v6
	v_mov_b32_e32 v63, v6
	v_mov_b32_e32 v16, v6
	v_mov_b32_e32 v17, v6
	v_mov_b32_e32 v18, v6
	v_mov_b32_e32 v19, v6
	v_mov_b32_e32 v20, v6
	v_mov_b32_e32 v21, v6
	v_mov_b32_e32 v22, v6
	v_mov_b32_e32 v23, v6
	v_mov_b32_e32 v32, v6
	v_mov_b32_e32 v33, v6
	v_mov_b32_e32 v34, v6
	v_mov_b32_e32 v35, v6
	v_mov_b32_e32 v36, v6
	v_mov_b32_e32 v37, v6
	v_mov_b32_e32 v38, v6
	v_mov_b32_e32 v39, v6
	v_mov_b32_e32 v48, v6
	v_mov_b32_e32 v49, v6
	v_mov_b32_e32 v50, v6
	v_mov_b32_e32 v51, v6
	v_mov_b32_e32 v52, v6
	v_mov_b32_e32 v53, v6
	v_mov_b32_e32 v54, v6
	v_mov_b32_e32 v55, v6
	v_mov_b32_e32 v64, v6
	v_mov_b32_e32 v65, v6
	v_mov_b32_e32 v66, v6
	v_mov_b32_e32 v67, v6
	v_mov_b32_e32 v68, v6
	v_mov_b32_e32 v69, v6
	v_mov_b32_e32 v70, v6
	v_mov_b32_e32 v71, v6
	v_mov_b32_e32 v72, v6
	v_mov_b32_e32 v73, v6
	v_mov_b32_e32 v74, v6
	v_mov_b32_e32 v75, v6
	v_mov_b32_e32 v76, v6
	v_mov_b32_e32 v77, v6
	v_mov_b32_e32 v78, v6
	v_mov_b32_e32 v79, v6
	v_mov_b32_e32 v88, v6
	v_mov_b32_e32 v89, v6
	v_mov_b32_e32 v90, v6
	v_mov_b32_e32 v91, v6
	v_mov_b32_e32 v100, v6
	v_mov_b32_e32 v101, v6
	v_mov_b32_e32 v102, v6
	v_mov_b32_e32 v103, v6
	v_mov_b32_e32 v152, v6
	v_mov_b32_e32 v153, v6
	v_mov_b32_e32 v154, v6
	v_mov_b32_e32 v155, v6
	v_mov_b32_e32 v156, v6
	v_mov_b32_e32 v157, v6
	v_mov_b32_e32 v158, v6
	v_mov_b32_e32 v159, v6
	v_mov_b32_e32 v168, v6
	v_mov_b32_e32 v169, v6
	v_mov_b32_e32 v170, v6
	v_mov_b32_e32 v171, v6
	v_mov_b32_e32 v172, v6
	v_mov_b32_e32 v173, v6
	v_mov_b32_e32 v174, v6
	v_mov_b32_e32 v175, v6
	v_mov_b32_e32 v80, v6
	v_mov_b32_e32 v81, v6
	v_mov_b32_e32 v82, v6
	v_mov_b32_e32 v83, v6
	v_mov_b32_e32 v84, v6
	v_mov_b32_e32 v85, v6
	v_mov_b32_e32 v86, v6
	v_mov_b32_e32 v87, v6
	v_mov_b32_e32 v136, v6
	v_mov_b32_e32 v137, v6
	v_mov_b32_e32 v138, v6
	v_mov_b32_e32 v139, v6
	v_mov_b32_e32 v148, v6
	v_mov_b32_e32 v149, v6
	v_mov_b32_e32 v150, v6
	v_mov_b32_e32 v151, v6
	v_mov_b32_e32 v160, v6
	v_mov_b32_e32 v161, v6
	v_mov_b32_e32 v162, v6
	v_mov_b32_e32 v163, v6
	v_mov_b32_e32 v164, v6
	v_mov_b32_e32 v165, v6
	v_mov_b32_e32 v166, v6
	v_mov_b32_e32 v167, v6
	v_mov_b32_e32 v176, v6
	v_mov_b32_e32 v177, v6
	v_mov_b32_e32 v178, v6
	v_mov_b32_e32 v179, v6
	v_mov_b32_e32 v180, v6
	v_mov_b32_e32 v181, v6
	v_mov_b32_e32 v182, v6
	v_mov_b32_e32 v183, v6
	s_branch .LBB0_1417
	.p2align	6

.LBB0_1773:
	s_ashr_i32 s83, s82, 31
	s_lshl_b64 s[2:3], s[82:83], 19
	s_add_u32 s58, s10, s2
	s_addc_u32 s59, s11, s3
	s_and_b64 s[2:3], s[52:53], exec
	s_cselect_b32 s4, s59, s49
	s_cselect_b32 s5, s58, s48
	s_ashr_i32 s9, s8, 31
	s_lshl_b64 s[2:3], s[8:9], 19
	s_add_u32 s2, s61, s2
	v_readlane_b32 s9, v250, 10
	s_addc_u32 s3, s9, s3
	s_and_b64 s[10:11], s[52:53], exec
	s_cselect_b32 s9, s3, s21
	s_cselect_b32 s12, s2, s20
	s_mov_b32 s13, -2
	s_mov_b64 s[38:39], 0
	.p2align	6

.LBB0_1928:
	s_add_u32 s4, s10, 0x100
	s_addc_u32 s5, s11, 0
	s_add_u32 s12, s82, 0x100
	s_addc_u32 s13, s83, 0
	s_add_u32 s42, s42, 0x100
	s_addc_u32 s43, s43, 0
	v_mov_b32_e32 v14, v15
	s_add_u32 s82, s10, 0xb0080
	v_mov_b32_e32 v16, v15
	v_mov_b32_e32 v17, v15
	v_mov_b32_e32 v6, 0
	v_mov_b64_e32 v[2:3], v[14:15]
	s_addc_u32 s83, s11, 0
	s_mov_b32 s17, -2
	v_mov_b64_e32 v[4:5], v[16:17]
	v_mov_b32_e32 v7, v6
	v_mov_b32_e32 v8, v6
	v_mov_b32_e32 v9, v6
	v_mov_b32_e32 v10, v6
	v_mov_b32_e32 v11, v6
	v_mov_b32_e32 v12, v6
	v_mov_b32_e32 v13, v6
	v_mov_b32_e32 v24, v6
	v_mov_b32_e32 v25, v6
	v_mov_b32_e32 v26, v6
	v_mov_b32_e32 v27, v6
	v_mov_b32_e32 v28, v6
	v_mov_b32_e32 v29, v6
	v_mov_b32_e32 v30, v6
	v_mov_b32_e32 v31, v6
	v_mov_b32_e32 v40, v6
	v_mov_b32_e32 v41, v6
	v_mov_b32_e32 v42, v6
	v_mov_b32_e32 v43, v6
	v_mov_b32_e32 v44, v6
	v_mov_b32_e32 v45, v6
	v_mov_b32_e32 v46, v6
	v_mov_b32_e32 v47, v6
	v_mov_b32_e32 v56, v6
	v_mov_b32_e32 v57, v6
	v_mov_b32_e32 v58, v6
	v_mov_b32_e32 v59, v6
	v_mov_b32_e32 v60, v6
	v_mov_b32_e32 v61, v6
	v_mov_b32_e32 v62, v6
	v_mov_b32_e32 v63, v6
	v_mov_b32_e32 v16, v6
	v_mov_b32_e32 v17, v6
	v_mov_b32_e32 v18, v6
	v_mov_b32_e32 v19, v6
	v_mov_b32_e32 v20, v6
	v_mov_b32_e32 v21, v6
	v_mov_b32_e32 v22, v6
	v_mov_b32_e32 v23, v6
	v_mov_b32_e32 v32, v6
	v_mov_b32_e32 v33, v6
	v_mov_b32_e32 v34, v6
	v_mov_b32_e32 v35, v6
	v_mov_b32_e32 v36, v6
	v_mov_b32_e32 v37, v6
	v_mov_b32_e32 v38, v6
	v_mov_b32_e32 v39, v6
	v_mov_b32_e32 v48, v6
	v_mov_b32_e32 v49, v6
	v_mov_b32_e32 v50, v6
	v_mov_b32_e32 v51, v6
	v_mov_b32_e32 v52, v6
	v_mov_b32_e32 v53, v6
	v_mov_b32_e32 v54, v6
	v_mov_b32_e32 v55, v6
	v_mov_b32_e32 v64, v6
	v_mov_b32_e32 v65, v6
	v_mov_b32_e32 v66, v6
	v_mov_b32_e32 v67, v6
	v_mov_b32_e32 v76, v6
	v_mov_b32_e32 v77, v6
	v_mov_b32_e32 v78, v6
	v_mov_b32_e32 v79, v6
	v_mov_b32_e32 v112, v6
	v_mov_b32_e32 v113, v6
	v_mov_b32_e32 v114, v6
	v_mov_b32_e32 v115, v6
	v_mov_b32_e32 v124, v6
	v_mov_b32_e32 v125, v6
	v_mov_b32_e32 v126, v6
	v_mov_b32_e32 v127, v6
	v_mov_b32_e32 v136, v6
	v_mov_b32_e32 v137, v6
	v_mov_b32_e32 v138, v6
	v_mov_b32_e32 v139, v6
	v_mov_b32_e32 v140, v6
	v_mov_b32_e32 v141, v6
	v_mov_b32_e32 v142, v6
	v_mov_b32_e32 v143, v6
	v_mov_b32_e32 v152, v6
	v_mov_b32_e32 v153, v6
	v_mov_b32_e32 v154, v6
	v_mov_b32_e32 v155, v6
	v_mov_b32_e32 v156, v6
	v_mov_b32_e32 v157, v6
	v_mov_b32_e32 v158, v6
	v_mov_b32_e32 v159, v6
	v_mov_b32_e32 v168, v6
	v_mov_b32_e32 v169, v6
	v_mov_b32_e32 v170, v6
	v_mov_b32_e32 v171, v6
	v_mov_b32_e32 v172, v6
	v_mov_b32_e32 v173, v6
	v_mov_b32_e32 v174, v6
	v_mov_b32_e32 v175, v6
	v_mov_b32_e32 v128, v6
	v_mov_b32_e32 v129, v6
	v_mov_b32_e32 v130, v6
	v_mov_b32_e32 v131, v6
	v_mov_b32_e32 v132, v6
	v_mov_b32_e32 v133, v6
	v_mov_b32_e32 v134, v6
	v_mov_b32_e32 v135, v6
	v_mov_b32_e32 v144, v6
	v_mov_b32_e32 v145, v6
	v_mov_b32_e32 v146, v6
	v_mov_b32_e32 v147, v6
	v_mov_b32_e32 v148, v6
	v_mov_b32_e32 v149, v6
	v_mov_b32_e32 v150, v6
	v_mov_b32_e32 v151, v6
	v_mov_b32_e32 v160, v6
	v_mov_b32_e32 v161, v6
	v_mov_b32_e32 v162, v6
	v_mov_b32_e32 v163, v6
	v_mov_b32_e32 v164, v6
	v_mov_b32_e32 v165, v6
	v_mov_b32_e32 v166, v6
	v_mov_b32_e32 v167, v6
	v_mov_b32_e32 v176, v6
	v_mov_b32_e32 v177, v6
	v_mov_b32_e32 v178, v6
	v_mov_b32_e32 v179, v6
	v_mov_b32_e32 v180, v6
	v_mov_b32_e32 v181, v6
	v_mov_b32_e32 v182, v6
	v_mov_b32_e32 v183, v6
	s_branch .LBB0_1930
	.p2align	6
